# baseline (speedup 1.0000x reference)
; #define STAGE8(P, BASE, br, kt) do { const char* _gb = (const char*)((BASE) + (size_t)(br) * K + (size_t)(kt) * BK8); \
;     __builtin_amdgcn_global_load_lds((const unsigned*)(_gb + soff0), (unsigned*)((char*)(P) + tid * 16), 16, 0, 0); \
;     __builtin_amdgcn_global_load_lds((const unsigned*)(_gb + soff1), (unsigned*)((char*)(P) + tid * 16 + 8192), 16, 0, 0); } while (0)
; #define WV8(n) asm volatile("s_waitcnt vmcnt(" #n ")" ::: "memory")
; #define BAR8 __builtin_amdgcn_s_barrier()
; __device__ __forceinline__ void gemm_core8(const u16* __restrict__ A, const u16* __restrict__ Bt, int K, int brow, int bcol,
;                                            f32x4 (&acc)[2][2][4][2], char* shmc, int wid_s) {
;     ...
;   unsigned soff0, soff1;
;   { int r_, c_; stage_rc8(tid * 16, r_, c_); soff0 = (unsigned)(r_ * K + c_) * 2u; stage_rc8(tid * 16 + 8192, r_, c_); soff1 = (unsigned)(r_ * K + c_) * 2u; }
;   bf16x8 At[4][2], B0[2][2], B1[2][2];
;   const int nt = K / BK8;
;   WV8(0); __syncthreads();
;   STAGE8(SB8(0, 0), Bt, bcol, 0); STAGE8(SA8(0, 0), A, brow, 0);
;   STAGE8(SB8(0, 1), Bt, bcol + HALF8, 0); STAGE8(SA8(0, 1), A, brow + HALF8, 0);
;   if (wr == 1) BAR8;
.LBB0_176:
	v_mbcnt_lo_u32_b32 v10, -1, 0
	v_mbcnt_hi_u32_b32 v10, -1, v10
	s_lshl_b32 s66, s11, 8
	v_add_u32_e32 v0, s95, v10
	v_ashrrev_i32_e32 v1, 31, v0
	v_lshrrev_b32_e32 v1, 26, v1
	v_lshlrev_b32_e32 v141, 4, v0
	v_add_u32_e32 v1, v0, v1
	v_bfe_i32 v0, v0, 27, 1
	v_lshrrev_b32_e32 v0, 22, v0
	v_add_u32_e32 v0, v141, v0
	v_and_b32_e32 v0, 0xfffffc00, v0
	v_sub_u32_e32 v0, v141, v0
	v_ashrrev_i32_e32 v2, 6, v1
	v_lshrrev_b32_e32 v1, 4, v0
	v_bitop3_b32 v0, v1, v0, 32 bitop3:0x6c
	v_ashrrev_i32_e32 v3, 31, v0
	v_lshrrev_b32_e32 v3, 26, v3
	v_add_u32_e32 v5, v0, v3
	v_lshlrev_b32_e32 v1, 3, v2
	v_ashrrev_i32_e32 v3, 6, v5
	v_and_b32_e32 v5, 0xc0, v5
	v_and_b32_e32 v1, 0xffff0, v1
	v_lshlrev_b32_e32 v4, 5, v2
	v_sub_u32_e32 v0, v0, v5
	v_add_u32_e32 v1, v3, v1
	v_and_b32_e32 v4, 32, v4
	v_ashrrev_i16_sdwa v0, v138, sext(v0) dst_sel:DWORD dst_unused:UNUSED_PAD src0_sel:DWORD src1_sel:BYTE_0
	v_bfe_i32 v5, v0, 0, 16
	v_lshl_or_b32 v0, v1, 11, v4
	v_add_u32_e32 v150, 0x2000, v141
	v_add_lshl_u32 v128, v0, v5, 1
	v_ashrrev_i32_e32 v0, 31, v150
	v_lshrrev_b32_e32 v0, 22, v0
	v_add_u32_e32 v0, v150, v0
	v_ashrrev_i32_e32 v6, 10, v0
	v_mul_i32_i24_e32 v0, 0x400, v6
	v_sub_u32_e32 v0, v150, v0
	v_lshrrev_b32_e32 v1, 4, v0
	s_ashr_i32 s67, s66, 31
	s_lshl_b32 s64, s10, 8
	v_bitop3_b32 v0, v1, v0, 32 bitop3:0x6c
	s_lshl_b64 s[68:69], s[66:67], 12
	v_ashrrev_i32_e32 v7, 31, v0
	s_add_u32 s72, s88, s68
	v_lshrrev_b32_e32 v7, 26, v7
	s_addc_u32 s73, s89, s69
	s_ashr_i32 s65, s64, 31
	v_add_u32_e32 v9, v0, v7
	s_lshl_b64 s[70:71], s[64:65], 12
	v_lshlrev_b32_e32 v1, 3, v6
	v_ashrrev_i32_e32 v7, 6, v9
	v_and_b32_e32 v9, 0xc0, v9
	s_add_u32 s78, s86, s70
	v_and_b32_e32 v1, 0xffff0, v1
	v_lshlrev_b32_e32 v8, 5, v6
	v_sub_u32_e32 v0, v0, v9
	v_add_u32_e32 v155, 0x10000, v141
	s_addc_u32 s79, s87, s71
	s_bitset1_b32 s66, 7
	v_add_u32_e32 v1, v7, v1
	v_and_b32_e32 v8, 32, v8
	v_ashrrev_i16_sdwa v0, v138, sext(v0) dst_sel:DWORD dst_unused:UNUSED_PAD src0_sel:DWORD src1_sel:BYTE_0
	v_readfirstlane_b32 s2, v155
	v_add_u32_e32 v156, 0x12000, v141
	s_ashr_i32 s67, s66, 31
	v_bfe_i32 v9, v0, 0, 16
	v_lshl_or_b32 v0, v1, 11, v8
	s_mov_b32 m0, s2
	v_readfirstlane_b32 s2, v156
	s_lshl_b64 s[66:67], s[66:67], 12
	v_add_lshl_u32 v0, v0, v9, 1
	s_barrier
	global_load_lds_dwordx4 v128, s[72:73]
	s_mov_b32 m0, s2
	v_readfirstlane_b32 s2, v141
	s_add_u32 s82, s88, s66
	global_load_lds_dwordx4 v0, s[72:73]
	s_mov_b32 m0, s2
	v_readfirstlane_b32 s2, v150
	s_addc_u32 s83, s89, s67
	v_add_u32_e32 v161, 0x14000, v141
	s_or_b32 s66, s64, 0x80
	global_load_lds_dwordx4 v128, s[78:79]
	s_mov_b32 m0, s2
	v_readfirstlane_b32 s2, v161
	v_add_u32_e32 v162, 0x16000, v141
	s_ashr_i32 s67, s66, 31
	global_load_lds_dwordx4 v0, s[78:79]
	s_mov_b32 m0, s2
	v_readfirstlane_b32 s2, v162
	s_lshl_b64 s[66:67], s[66:67], 12
	v_add_u32_e32 v163, 0x4000, v141
	global_load_lds_dwordx4 v128, s[82:83]
	s_mov_b32 m0, s2
	s_add_u32 s66, s86, s66
	v_readfirstlane_b32 s2, v163
	v_add_u32_e32 v164, 0x6000, v141
	global_load_lds_dwordx4 v0, s[82:83]
	s_addc_u32 s67, s87, s67
	s_mov_b32 m0, s2
	v_readfirstlane_b32 s2, v164
	global_load_lds_dwordx4 v128, s[66:67]
	s_mov_b32 m0, s2
	s_andn2_b64 vcc, exec, s[50:51]
	global_load_lds_dwordx4 v0, s[66:67]
	s_cbranch_vccnz .LBB0_178
	s_barrier

; #define STAGE8(P, BASE, br, kt) do { const char* _gb = (const char*)((BASE) + (size_t)(br) * K + (size_t)(kt) * BK8); \
;     __builtin_amdgcn_global_load_lds((const unsigned*)(_gb + soff0), (unsigned*)((char*)(P) + tid * 16), 16, 0, 0); \
;     __builtin_amdgcn_global_load_lds((const unsigned*)(_gb + soff1), (unsigned*)((char*)(P) + tid * 16 + 8192), 16, 0, 0); } while (0)
; #define WV8(n) asm volatile("s_waitcnt vmcnt(" #n ")" ::: "memory")
; #define BAR8 __builtin_amdgcn_s_barrier()
; __device__ __forceinline__ void gemm_core8(const u16* __restrict__ A, const u16* __restrict__ Bt, int K, int brow, int bcol,
;                                            f32x4 (&acc)[2][2][4][2], char* shmc, int wid_s) {
;     ...
;   unsigned soff0, soff1;
;   { int r_, c_; stage_rc8(tid * 16, r_, c_); soff0 = (unsigned)(r_ * K + c_) * 2u; stage_rc8(tid * 16 + 8192, r_, c_); soff1 = (unsigned)(r_ * K + c_) * 2u; }
;   bf16x8 At[4][2], B0[2][2], B1[2][2];
;   const int nt = K / BK8;
;   WV8(0); __syncthreads();
;   STAGE8(SB8(0, 0), Bt, bcol, 0); STAGE8(SA8(0, 0), A, brow, 0);
;   STAGE8(SB8(0, 1), Bt, bcol + HALF8, 0); STAGE8(SA8(0, 1), A, brow + HALF8, 0);
;   if (wr == 1) BAR8;
.LBB0_933:
	v_mbcnt_lo_u32_b32 v10, -1, 0
	v_mbcnt_hi_u32_b32 v10, -1, v10
	s_lshl_b32 s54, s92, 8
	v_add_u32_e32 v0, s73, v10
	v_ashrrev_i32_e32 v1, 31, v0
	v_lshrrev_b32_e32 v1, 26, v1
	v_lshlrev_b32_e32 v139, 4, v0
	v_add_u32_e32 v1, v0, v1
	v_bfe_i32 v0, v0, 27, 1
	v_lshrrev_b32_e32 v0, 22, v0
	v_add_u32_e32 v0, v139, v0
	v_and_b32_e32 v0, 0xfffffc00, v0
	v_sub_u32_e32 v0, v139, v0
	v_ashrrev_i32_e32 v2, 6, v1
	v_lshrrev_b32_e32 v1, 4, v0
	v_bitop3_b32 v0, v1, v0, 32 bitop3:0x6c
	v_ashrrev_i32_e32 v3, 31, v0
	v_lshrrev_b32_e32 v3, 26, v3
	v_add_u32_e32 v5, v0, v3
	v_lshlrev_b32_e32 v1, 3, v2
	v_ashrrev_i32_e32 v3, 6, v5
	v_and_b32_e32 v5, 0xc0, v5
	v_and_b32_e32 v1, 0x3ffff0, v1
	v_lshlrev_b32_e32 v4, 5, v2
	v_sub_u32_e32 v0, v0, v5
	v_add_u32_e32 v1, v3, v1
	v_and_b32_e32 v4, 32, v4
	v_ashrrev_i16_sdwa v0, v138, sext(v0) dst_sel:DWORD dst_unused:UNUSED_PAD src0_sel:DWORD src1_sel:BYTE_0
	v_bfe_i32 v5, v0, 0, 16
	v_lshl_or_b32 v0, v1, 9, v4
	v_add_u32_e32 v148, 0x2000, v139
	v_add_lshl_u32 v128, v0, v5, 1
	v_ashrrev_i32_e32 v0, 31, v148
	v_lshrrev_b32_e32 v0, 22, v0
	v_add_u32_e32 v0, v148, v0
	v_ashrrev_i32_e32 v6, 10, v0
	v_mul_i32_i24_e32 v0, 0x400, v6
	v_sub_u32_e32 v0, v148, v0
	s_ashr_i32 s55, s54, 31
	s_lshl_b32 s52, s91, 8
	v_lshrrev_b32_e32 v1, 4, v0
	s_lshl_b64 s[56:57], s[54:55], 10
	v_add_u32_e32 v153, 0x10000, v139
	v_bitop3_b32 v0, v1, v0, 32 bitop3:0x6c
	s_add_u32 s60, s68, s56
	v_readfirstlane_b32 s53, v153
	v_add_u32_e32 v154, 0x12000, v139
	v_ashrrev_i32_e32 v7, 31, v0
	s_addc_u32 s61, s69, s57
	s_mov_b32 m0, s53
	v_readfirstlane_b32 s53, v154
	v_lshrrev_b32_e32 v7, 26, v7
	s_waitcnt vmcnt(63) expcnt(7) lgkmcnt(15)
	s_barrier
	global_load_lds_dwordx4 v128, s[60:61]
	s_mov_b32 m0, s53
	s_ashr_i32 s53, s52, 31
	v_add_u32_e32 v9, v0, v7
	s_lshl_b64 s[58:59], s[52:53], 10
	v_lshlrev_b32_e32 v1, 3, v6
	v_ashrrev_i32_e32 v7, 6, v9
	v_and_b32_e32 v9, 0xc0, v9
	s_add_u32 s62, s66, s58
	v_and_b32_e32 v1, 0x3ffff0, v1
	v_lshlrev_b32_e32 v8, 5, v6
	v_sub_u32_e32 v0, v0, v9
	s_addc_u32 s63, s67, s59
	s_bitset1_b32 s54, 7
	v_add_u32_e32 v1, v7, v1
	v_and_b32_e32 v8, 32, v8
	v_ashrrev_i16_sdwa v0, v138, sext(v0) dst_sel:DWORD dst_unused:UNUSED_PAD src0_sel:DWORD src1_sel:BYTE_0
	s_ashr_i32 s55, s54, 31
	v_bfe_i32 v9, v0, 0, 16
	v_lshl_or_b32 v0, v1, 9, v8
	s_lshl_b64 s[54:55], s[54:55], 10
	v_add_lshl_u32 v0, v0, v9, 1
	v_readfirstlane_b32 s53, v139
	s_add_u32 s64, s68, s54
	global_load_lds_dwordx4 v0, s[60:61]
	s_mov_b32 m0, s53
	v_readfirstlane_b32 s53, v148
	s_addc_u32 s65, s69, s55
	v_add_u32_e32 v159, 0x14000, v139
	s_or_b32 s54, s52, 0x80
	global_load_lds_dwordx4 v128, s[62:63]
	s_mov_b32 m0, s53
	v_readfirstlane_b32 s53, v159
	v_add_u32_e32 v160, 0x16000, v139
	s_ashr_i32 s55, s54, 31
	global_load_lds_dwordx4 v0, s[62:63]
	s_mov_b32 m0, s53
	v_readfirstlane_b32 s53, v160
	s_lshl_b64 s[54:55], s[54:55], 10
	v_add_u32_e32 v161, 0x4000, v139
	global_load_lds_dwordx4 v128, s[64:65]
	s_mov_b32 m0, s53
	s_add_u32 s54, s66, s54
	v_readfirstlane_b32 s53, v161
	v_add_u32_e32 v162, 0x6000, v139
	global_load_lds_dwordx4 v0, s[64:65]
	s_addc_u32 s55, s67, s55
	s_mov_b32 m0, s53
	v_readfirstlane_b32 s53, v162
	global_load_lds_dwordx4 v128, s[54:55]
	s_mov_b32 m0, s53
	s_and_b64 vcc, exec, s[0:1]
	global_load_lds_dwordx4 v0, s[54:55]
	s_cbranch_vccnz .LBB0_935
	s_barrier

; #define STAGE8(P, BASE, br, kt) do { const char* _gb = (const char*)((BASE) + (size_t)(br) * K + (size_t)(kt) * BK8); \
;     __builtin_amdgcn_global_load_lds((const unsigned*)(_gb + soff0), (unsigned*)((char*)(P) + tid * 16), 16, 0, 0); \
;     __builtin_amdgcn_global_load_lds((const unsigned*)(_gb + soff1), (unsigned*)((char*)(P) + tid * 16 + 8192), 16, 0, 0); } while (0)
; #define WV8(n) asm volatile("s_waitcnt vmcnt(" #n ")" ::: "memory")
; #define BAR8 __builtin_amdgcn_s_barrier()
; __device__ __forceinline__ void gemm_core8(const u16* __restrict__ A, const u16* __restrict__ Bt, int K, int brow, int bcol,
;                                            f32x4 (&acc)[2][2][4][2], char* shmc, int wid_s) {
;     ...
;   unsigned soff0, soff1;
;   { int r_, c_; stage_rc8(tid * 16, r_, c_); soff0 = (unsigned)(r_ * K + c_) * 2u; stage_rc8(tid * 16 + 8192, r_, c_); soff1 = (unsigned)(r_ * K + c_) * 2u; }
;   bf16x8 At[4][2], B0[2][2], B1[2][2];
;   const int nt = K / BK8;
;   WV8(0); __syncthreads();
;   STAGE8(SB8(0, 0), Bt, bcol, 0); STAGE8(SA8(0, 0), A, brow, 0);
;   STAGE8(SB8(0, 1), Bt, bcol + HALF8, 0); STAGE8(SA8(0, 1), A, brow + HALF8, 0);
;   if (wr == 1) BAR8;
.LBB0_950:
	v_mbcnt_lo_u32_b32 v10, -1, 0
	v_mbcnt_hi_u32_b32 v10, -1, v10
	s_lshl_b32 s54, s93, 8
	v_add_u32_e32 v0, s73, v10
	v_ashrrev_i32_e32 v1, 31, v0
	v_lshrrev_b32_e32 v1, 26, v1
	v_lshlrev_b32_e32 v139, 4, v0
	v_add_u32_e32 v1, v0, v1
	v_bfe_i32 v0, v0, 27, 1
	v_lshrrev_b32_e32 v0, 22, v0
	v_add_u32_e32 v0, v139, v0
	v_and_b32_e32 v0, 0xfffffc00, v0
	v_sub_u32_e32 v0, v139, v0
	v_ashrrev_i32_e32 v2, 6, v1
	v_lshrrev_b32_e32 v1, 4, v0
	v_bitop3_b32 v0, v1, v0, 32 bitop3:0x6c
	v_ashrrev_i32_e32 v3, 31, v0
	v_lshrrev_b32_e32 v3, 26, v3
	v_add_u32_e32 v5, v0, v3
	v_lshlrev_b32_e32 v1, 3, v2
	v_ashrrev_i32_e32 v3, 6, v5
	v_and_b32_e32 v5, 0xc0, v5
	v_and_b32_e32 v1, 0x1ffff0, v1
	v_lshlrev_b32_e32 v4, 5, v2
	v_sub_u32_e32 v0, v0, v5
	v_add_u32_e32 v1, v3, v1
	v_and_b32_e32 v4, 32, v4
	v_ashrrev_i16_sdwa v0, v138, sext(v0) dst_sel:DWORD dst_unused:UNUSED_PAD src0_sel:DWORD src1_sel:BYTE_0
	v_bfe_i32 v5, v0, 0, 16
	v_lshl_or_b32 v0, v1, 10, v4
	v_add_u32_e32 v148, 0x2000, v139
	v_add_lshl_u32 v128, v0, v5, 1
	v_ashrrev_i32_e32 v0, 31, v148
	v_lshrrev_b32_e32 v0, 22, v0
	v_add_u32_e32 v0, v148, v0
	v_ashrrev_i32_e32 v6, 10, v0
	v_mul_i32_i24_e32 v0, 0x400, v6
	v_sub_u32_e32 v0, v148, v0
	s_ashr_i32 s55, s54, 31
	s_lshl_b32 s52, s92, 8
	v_lshrrev_b32_e32 v1, 4, v0
	s_lshl_b64 s[56:57], s[54:55], 11
	v_add_u32_e32 v153, 0x10000, v139
	v_bitop3_b32 v0, v1, v0, 32 bitop3:0x6c
	s_add_u32 s60, s67, s56
	v_readfirstlane_b32 s53, v153
	v_add_u32_e32 v154, 0x12000, v139
	v_ashrrev_i32_e32 v7, 31, v0
	s_addc_u32 s61, s68, s57
	s_mov_b32 m0, s53
	v_readfirstlane_b32 s53, v154
	v_lshrrev_b32_e32 v7, 26, v7
	s_waitcnt vmcnt(63) expcnt(7) lgkmcnt(15)
	s_barrier
	global_load_lds_dwordx4 v128, s[60:61]
	s_mov_b32 m0, s53
	s_ashr_i32 s53, s52, 31
	v_add_u32_e32 v9, v0, v7
	s_lshl_b64 s[58:59], s[52:53], 11
	v_lshlrev_b32_e32 v1, 3, v6
	v_ashrrev_i32_e32 v7, 6, v9
	v_and_b32_e32 v9, 0xc0, v9
	s_add_u32 s62, s3, s58
	v_and_b32_e32 v1, 0x1ffff0, v1
	v_lshlrev_b32_e32 v8, 5, v6
	v_sub_u32_e32 v0, v0, v9
	s_addc_u32 s63, s66, s59
	s_bitset1_b32 s54, 7
	v_add_u32_e32 v1, v7, v1
	v_and_b32_e32 v8, 32, v8
	v_ashrrev_i16_sdwa v0, v138, sext(v0) dst_sel:DWORD dst_unused:UNUSED_PAD src0_sel:DWORD src1_sel:BYTE_0
	s_ashr_i32 s55, s54, 31
	v_bfe_i32 v9, v0, 0, 16
	v_lshl_or_b32 v0, v1, 10, v8
	s_lshl_b64 s[54:55], s[54:55], 11
	v_add_lshl_u32 v0, v0, v9, 1
	v_readfirstlane_b32 s53, v139
	s_add_u32 s64, s67, s54
	global_load_lds_dwordx4 v0, s[60:61]
	s_mov_b32 m0, s53
	v_readfirstlane_b32 s53, v148
	s_addc_u32 s65, s68, s55
	v_add_u32_e32 v159, 0x14000, v139
	s_or_b32 s54, s52, 0x80
	global_load_lds_dwordx4 v128, s[62:63]
	s_mov_b32 m0, s53
	v_readfirstlane_b32 s53, v159
	v_add_u32_e32 v160, 0x16000, v139
	s_ashr_i32 s55, s54, 31
	global_load_lds_dwordx4 v0, s[62:63]
	s_mov_b32 m0, s53
	v_readfirstlane_b32 s53, v160
	s_lshl_b64 s[54:55], s[54:55], 11
	v_add_u32_e32 v161, 0x4000, v139
	global_load_lds_dwordx4 v128, s[64:65]
	s_mov_b32 m0, s53
	s_add_u32 s54, s3, s54
	v_readfirstlane_b32 s53, v161
	v_add_u32_e32 v162, 0x6000, v139
	global_load_lds_dwordx4 v0, s[64:65]
	s_addc_u32 s55, s66, s55
	s_mov_b32 m0, s53
	v_readfirstlane_b32 s53, v162
	global_load_lds_dwordx4 v128, s[54:55]
	s_mov_b32 m0, s53
	s_and_b64 vcc, exec, s[0:1]
	global_load_lds_dwordx4 v0, s[54:55]
	s_cbranch_vccnz .LBB0_952
	s_barrier

; #define STAGE8(P, BASE, br, kt) do { const char* _gb = (const char*)((BASE) + (size_t)(br) * K + (size_t)(kt) * BK8); \
;     __builtin_amdgcn_global_load_lds((const unsigned*)(_gb + soff0), (unsigned*)((char*)(P) + tid * 16), 16, 0, 0); \
;     __builtin_amdgcn_global_load_lds((const unsigned*)(_gb + soff1), (unsigned*)((char*)(P) + tid * 16 + 8192), 16, 0, 0); } while (0)
; #define WV8(n) asm volatile("s_waitcnt vmcnt(" #n ")" ::: "memory")
; #define BAR8 __builtin_amdgcn_s_barrier()
; __device__ __forceinline__ void gemm_core8(const u16* __restrict__ A, const u16* __restrict__ Bt, int K, int brow, int bcol,
;                                            f32x4 (&acc)[2][2][4][2], char* shmc, int wid_s) {
;     ...
;   unsigned soff0, soff1;
;   { int r_, c_; stage_rc8(tid * 16, r_, c_); soff0 = (unsigned)(r_ * K + c_) * 2u; stage_rc8(tid * 16 + 8192, r_, c_); soff1 = (unsigned)(r_ * K + c_) * 2u; }
;   bf16x8 At[4][2], B0[2][2], B1[2][2];
;   const int nt = K / BK8;
;   WV8(0); __syncthreads();
;   STAGE8(SB8(0, 0), Bt, bcol, 0); STAGE8(SA8(0, 0), A, brow, 0);
;   STAGE8(SB8(0, 1), Bt, bcol + HALF8, 0); STAGE8(SA8(0, 1), A, brow + HALF8, 0);
;   if (wr == 1) BAR8;
.LBB0_989:
	v_mbcnt_lo_u32_b32 v10, -1, 0
	v_mbcnt_hi_u32_b32 v10, -1, v10
	s_lshl_b32 s54, s94, 8
	v_add_u32_e32 v0, s73, v10
	v_ashrrev_i32_e32 v1, 31, v0
	v_lshrrev_b32_e32 v1, 26, v1
	v_lshlrev_b32_e32 v139, 4, v0
	v_add_u32_e32 v1, v0, v1
	v_bfe_i32 v0, v0, 27, 1
	v_lshrrev_b32_e32 v0, 22, v0
	v_add_u32_e32 v0, v139, v0
	v_and_b32_e32 v0, 0xfffffc00, v0
	v_sub_u32_e32 v0, v139, v0
	v_ashrrev_i32_e32 v2, 6, v1
	v_lshrrev_b32_e32 v1, 4, v0
	v_bitop3_b32 v0, v1, v0, 32 bitop3:0x6c
	v_ashrrev_i32_e32 v3, 31, v0
	v_lshrrev_b32_e32 v3, 26, v3
	v_add_u32_e32 v5, v0, v3
	v_lshlrev_b32_e32 v1, 3, v2
	v_ashrrev_i32_e32 v3, 6, v5
	v_and_b32_e32 v5, 0xc0, v5
	v_and_b32_e32 v1, 0xffff0, v1
	v_lshlrev_b32_e32 v4, 5, v2
	v_sub_u32_e32 v0, v0, v5
	v_add_u32_e32 v1, v3, v1
	v_and_b32_e32 v4, 32, v4
	v_ashrrev_i16_sdwa v0, v138, sext(v0) dst_sel:DWORD dst_unused:UNUSED_PAD src0_sel:DWORD src1_sel:BYTE_0
	v_bfe_i32 v5, v0, 0, 16
	v_lshl_or_b32 v0, v1, 11, v4
	v_add_u32_e32 v148, 0x2000, v139
	v_add_lshl_u32 v128, v0, v5, 1
	v_ashrrev_i32_e32 v0, 31, v148
	v_lshrrev_b32_e32 v0, 22, v0
	v_add_u32_e32 v0, v148, v0
	v_ashrrev_i32_e32 v6, 10, v0
	v_mul_i32_i24_e32 v0, 0x400, v6
	v_sub_u32_e32 v0, v148, v0
	s_ashr_i32 s55, s54, 31
	s_lshl_b32 s52, s93, 8
	v_lshrrev_b32_e32 v1, 4, v0
	s_lshl_b64 s[56:57], s[54:55], 12
	v_add_u32_e32 v153, 0x10000, v139
	v_bitop3_b32 v0, v1, v0, 32 bitop3:0x6c
	s_add_u32 s60, s68, s56
	v_readfirstlane_b32 s53, v153
	v_add_u32_e32 v154, 0x12000, v139
	v_ashrrev_i32_e32 v7, 31, v0
	s_addc_u32 s61, s69, s57
	s_mov_b32 m0, s53
	v_readfirstlane_b32 s53, v154
	v_lshrrev_b32_e32 v7, 26, v7
	s_barrier
	global_load_lds_dwordx4 v128, s[60:61]
	s_mov_b32 m0, s53
	s_ashr_i32 s53, s52, 31
	v_add_u32_e32 v9, v0, v7
	s_lshl_b64 s[58:59], s[52:53], 12
	v_lshlrev_b32_e32 v1, 3, v6
	v_ashrrev_i32_e32 v7, 6, v9
	v_and_b32_e32 v9, 0xc0, v9
	s_add_u32 s62, s66, s58
	v_and_b32_e32 v1, 0xffff0, v1
	v_lshlrev_b32_e32 v8, 5, v6
	v_sub_u32_e32 v0, v0, v9
	s_addc_u32 s63, s67, s59
	s_bitset1_b32 s54, 7
	v_add_u32_e32 v1, v7, v1
	v_and_b32_e32 v8, 32, v8
	v_ashrrev_i16_sdwa v0, v138, sext(v0) dst_sel:DWORD dst_unused:UNUSED_PAD src0_sel:DWORD src1_sel:BYTE_0
	s_ashr_i32 s55, s54, 31
	v_bfe_i32 v9, v0, 0, 16
	v_lshl_or_b32 v0, v1, 11, v8
	s_lshl_b64 s[54:55], s[54:55], 12
	v_add_lshl_u32 v0, v0, v9, 1
	v_readfirstlane_b32 s53, v139
	s_add_u32 s64, s68, s54
	global_load_lds_dwordx4 v0, s[60:61]
	s_mov_b32 m0, s53
	v_readfirstlane_b32 s53, v148
	s_addc_u32 s65, s69, s55
	v_add_u32_e32 v159, 0x14000, v139
	s_or_b32 s54, s52, 0x80
	global_load_lds_dwordx4 v128, s[62:63]
	s_mov_b32 m0, s53
	v_readfirstlane_b32 s53, v159
	v_add_u32_e32 v160, 0x16000, v139
	s_ashr_i32 s55, s54, 31
	global_load_lds_dwordx4 v0, s[62:63]
	s_mov_b32 m0, s53
	v_readfirstlane_b32 s53, v160
	s_lshl_b64 s[54:55], s[54:55], 12
	v_add_u32_e32 v161, 0x4000, v139
	global_load_lds_dwordx4 v128, s[64:65]
	s_mov_b32 m0, s53
	s_add_u32 s54, s66, s54
	v_readfirstlane_b32 s53, v161
	v_add_u32_e32 v162, 0x6000, v139
	global_load_lds_dwordx4 v0, s[64:65]
	s_addc_u32 s55, s67, s55
	s_mov_b32 m0, s53
	v_readfirstlane_b32 s53, v162
	global_load_lds_dwordx4 v128, s[54:55]
	s_mov_b32 m0, s53
	s_and_b64 vcc, exec, s[0:1]
	global_load_lds_dwordx4 v0, s[54:55]
	s_cbranch_vccnz .LBB0_991
	s_barrier

; #define STAGE8(P, BASE, br, kt) do { const char* _gb = (const char*)((BASE) + (size_t)(br) * K + (size_t)(kt) * BK8); \
;     __builtin_amdgcn_global_load_lds((const unsigned*)(_gb + soff0), (unsigned*)((char*)(P) + tid * 16), 16, 0, 0); \
;     __builtin_amdgcn_global_load_lds((const unsigned*)(_gb + soff1), (unsigned*)((char*)(P) + tid * 16 + 8192), 16, 0, 0); } while (0)
; #define WV8(n) asm volatile("s_waitcnt vmcnt(" #n ")" ::: "memory")
; #define BAR8 __builtin_amdgcn_s_barrier()
; __device__ __forceinline__ void gemm_core8(const u16* __restrict__ A, const u16* __restrict__ Bt, int K, int brow, int bcol,
;                                            f32x4 (&acc)[2][2][4][2], char* shmc, int wid_s) {
;     ...
;   unsigned soff0, soff1;
;   { int r_, c_; stage_rc8(tid * 16, r_, c_); soff0 = (unsigned)(r_ * K + c_) * 2u; stage_rc8(tid * 16 + 8192, r_, c_); soff1 = (unsigned)(r_ * K + c_) * 2u; }
;   bf16x8 At[4][2], B0[2][2], B1[2][2];
;   const int nt = K / BK8;
;   WV8(0); __syncthreads();
;   STAGE8(SB8(0, 0), Bt, bcol, 0); STAGE8(SA8(0, 0), A, brow, 0);
;   STAGE8(SB8(0, 1), Bt, bcol + HALF8, 0); STAGE8(SA8(0, 1), A, brow + HALF8, 0);
;   if (wr == 1) BAR8;
.LBB0_1054:
	v_mbcnt_lo_u32_b32 v10, -1, 0
	v_mbcnt_hi_u32_b32 v10, -1, v10
	s_lshl_b32 s0, s93, 8
	v_add_u32_e32 v0, s74, v10
	v_ashrrev_i32_e32 v1, 31, v0
	v_lshrrev_b32_e32 v1, 26, v1
	v_lshlrev_b32_e32 v138, 4, v0
	v_add_u32_e32 v1, v0, v1
	v_bfe_i32 v0, v0, 27, 1
	v_lshrrev_b32_e32 v0, 22, v0
	v_add_u32_e32 v0, v138, v0
	v_and_b32_e32 v0, 0xfffffc00, v0
	v_sub_u32_e32 v0, v138, v0
	v_ashrrev_i32_e32 v2, 6, v1
	v_lshrrev_b32_e32 v1, 4, v0
	v_bitop3_b32 v0, v1, v0, 32 bitop3:0x6c
	v_ashrrev_i32_e32 v3, 31, v0
	v_lshrrev_b32_e32 v3, 26, v3
	v_add_u32_e32 v5, v0, v3
	v_lshlrev_b32_e32 v1, 3, v2
	v_ashrrev_i32_e32 v3, 6, v5
	v_and_b32_e32 v5, 0xc0, v5
	v_and_b32_e32 v1, 0xffff0, v1
	v_lshlrev_b32_e32 v4, 5, v2
	v_sub_u32_e32 v0, v0, v5
	v_add_u32_e32 v1, v3, v1
	v_and_b32_e32 v4, 32, v4
	v_ashrrev_i16_sdwa v0, v154, sext(v0) dst_sel:DWORD dst_unused:UNUSED_PAD src0_sel:DWORD src1_sel:BYTE_0
	v_bfe_i32 v5, v0, 0, 16
	v_lshl_or_b32 v0, v1, 11, v4
	v_add_u32_e32 v147, 0x2000, v138
	v_add_lshl_u32 v128, v0, v5, 1
	v_ashrrev_i32_e32 v0, 31, v147
	v_lshrrev_b32_e32 v0, 22, v0
	v_add_u32_e32 v0, v147, v0
	v_ashrrev_i32_e32 v6, 10, v0
	v_mul_i32_i24_e32 v0, 0x400, v6
	v_sub_u32_e32 v0, v147, v0
	v_lshrrev_b32_e32 v1, 4, v0
	v_bitop3_b32 v0, v1, v0, 32 bitop3:0x6c
	v_ashrrev_i32_e32 v7, 31, v0
	v_lshrrev_b32_e32 v7, 26, v7
	v_add_u32_e32 v9, v0, v7
	s_ashr_i32 s1, s0, 31
	s_lshl_b32 s54, s52, 8
	v_lshlrev_b32_e32 v1, 3, v6
	v_ashrrev_i32_e32 v7, 6, v9
	v_and_b32_e32 v9, 0xc0, v9
	s_lshl_b64 s[56:57], s[0:1], 12
	v_and_b32_e32 v1, 0xffff0, v1
	v_lshlrev_b32_e32 v8, 5, v6
	v_sub_u32_e32 v0, v0, v9
	s_add_u32 s60, s30, s56
	v_add_u32_e32 v152, 0x10000, v138
	v_add_u32_e32 v1, v7, v1
	v_and_b32_e32 v8, 32, v8
	v_ashrrev_i16_sdwa v0, v154, sext(v0) dst_sel:DWORD dst_unused:UNUSED_PAD src0_sel:DWORD src1_sel:BYTE_0
	s_addc_u32 s61, s31, s57
	v_readfirstlane_b32 s1, v152
	v_add_u32_e32 v153, 0x12000, v138
	s_ashr_i32 s55, s54, 31
	v_bfe_i32 v9, v0, 0, 16
	v_lshl_or_b32 v0, v1, 11, v8
	s_mov_b32 m0, s1
	v_readfirstlane_b32 s1, v153
	s_lshl_b64 s[58:59], s[54:55], 12
	v_add_lshl_u32 v0, v0, v9, 1
	s_waitcnt vmcnt(63) expcnt(7) lgkmcnt(15)
	s_barrier
	global_load_lds_dwordx4 v128, s[60:61]
	s_mov_b32 m0, s1
	s_add_u32 s62, s67, s58
	v_readfirstlane_b32 s1, v138
	global_load_lds_dwordx4 v0, s[60:61]
	s_addc_u32 s63, s68, s59
	s_mov_b32 m0, s1
	v_readfirstlane_b32 s1, v147
	s_bitset1_b32 s0, 7
	global_load_lds_dwordx4 v128, s[62:63]
	s_mov_b32 m0, s1
	s_ashr_i32 s1, s0, 31
	s_lshl_b64 s[0:1], s[0:1], 12
	v_add_u32_e32 v159, 0x14000, v138
	s_add_u32 s64, s30, s0
	v_readfirstlane_b32 s0, v159
	v_add_u32_e32 v160, 0x16000, v138
	global_load_lds_dwordx4 v0, s[62:63]
	s_addc_u32 s65, s31, s1
	s_mov_b32 m0, s0
	v_readfirstlane_b32 s0, v160
	global_load_lds_dwordx4 v128, s[64:65]
	s_mov_b32 m0, s0
	s_or_b32 s0, s54, 0x80
	s_ashr_i32 s1, s0, 31
	s_lshl_b64 s[0:1], s[0:1], 12
	v_add_u32_e32 v161, 0x4000, v138
	s_add_u32 s0, s67, s0
	v_readfirstlane_b32 s53, v161
	v_add_u32_e32 v162, 0x6000, v138
	global_load_lds_dwordx4 v0, s[64:65]
	s_addc_u32 s1, s68, s1
	s_mov_b32 m0, s53
	v_readfirstlane_b32 s53, v162
	global_load_lds_dwordx4 v128, s[0:1]
	s_mov_b32 m0, s53
	s_andn2_b64 vcc, exec, s[10:11]
	global_load_lds_dwordx4 v0, s[0:1]
	s_cbranch_vccnz .LBB0_1056
	s_barrier

; #define STAGE8(P, BASE, br, kt) do { const char* _gb = (const char*)((BASE) + (size_t)(br) * K + (size_t)(kt) * BK8); \
;     __builtin_amdgcn_global_load_lds((const unsigned*)(_gb + soff0), (unsigned*)((char*)(P) + tid * 16), 16, 0, 0); \
;     __builtin_amdgcn_global_load_lds((const unsigned*)(_gb + soff1), (unsigned*)((char*)(P) + tid * 16 + 8192), 16, 0, 0); } while (0)
; #define WV8(n) asm volatile("s_waitcnt vmcnt(" #n ")" ::: "memory")
; #define BAR8 __builtin_amdgcn_s_barrier()
; __device__ __forceinline__ void gemm_core8(const u16* __restrict__ A, const u16* __restrict__ Bt, int K, int brow, int bcol,
;                                            f32x4 (&acc)[2][2][4][2], char* shmc, int wid_s) {
;     ...
;   unsigned soff0, soff1;
;   { int r_, c_; stage_rc8(tid * 16, r_, c_); soff0 = (unsigned)(r_ * K + c_) * 2u; stage_rc8(tid * 16 + 8192, r_, c_); soff1 = (unsigned)(r_ * K + c_) * 2u; }
;   bf16x8 At[4][2], B0[2][2], B1[2][2];
;   const int nt = K / BK8;
;   WV8(0); __syncthreads();
;   STAGE8(SB8(0, 0), Bt, bcol, 0); STAGE8(SA8(0, 0), A, brow, 0);
;   STAGE8(SB8(0, 1), Bt, bcol + HALF8, 0); STAGE8(SA8(0, 1), A, brow + HALF8, 0);
;   if (wr == 1) BAR8;
.LBB0_1331:
	v_mbcnt_lo_u32_b32 v10, -1, 0
	v_mbcnt_hi_u32_b32 v10, -1, v10
	s_lshl_b32 s81, s79, 8
	v_add_u32_e32 v0, s57, v10
	v_ashrrev_i32_e32 v1, 31, v0
	v_lshrrev_b32_e32 v1, 26, v1
	v_lshlrev_b32_e32 v139, 4, v0
	v_add_u32_e32 v1, v0, v1
	v_bfe_i32 v0, v0, 27, 1
	v_lshrrev_b32_e32 v0, 22, v0
	v_add_u32_e32 v0, v139, v0
	v_and_b32_e32 v0, 0xfffffc00, v0
	v_sub_u32_e32 v0, v139, v0
	v_ashrrev_i32_e32 v2, 6, v1
	v_lshrrev_b32_e32 v1, 4, v0
	v_bitop3_b32 v0, v1, v0, 32 bitop3:0x6c
	v_ashrrev_i32_e32 v3, 31, v0
	v_lshrrev_b32_e32 v3, 26, v3
	v_add_u32_e32 v5, v0, v3
	v_lshlrev_b32_e32 v1, 3, v2
	v_ashrrev_i32_e32 v3, 6, v5
	v_and_b32_e32 v5, 0xc0, v5
	v_and_b32_e32 v1, 0x1fffff0, v1
	v_sub_u32_e32 v0, v0, v5
	v_add_u32_e32 v1, v3, v1
	v_lshlrev_b32_e32 v4, 5, v2
	v_ashrrev_i16_sdwa v0, v138, sext(v0) dst_sel:DWORD dst_unused:UNUSED_PAD src0_sel:DWORD src1_sel:BYTE_0
	v_and_b32_e32 v4, 32, v4
	v_bfe_i32 v5, v0, 0, 16
	v_mul_lo_u32 v0, v1, s70
	v_or_b32_e32 v0, v0, v4
	v_add_u32_e32 v147, 0x2000, v139
	v_add_lshl_u32 v128, v0, v5, 1
	v_ashrrev_i32_e32 v0, 31, v147
	v_lshrrev_b32_e32 v0, 22, v0
	v_add_u32_e32 v0, v147, v0
	v_ashrrev_i32_e32 v6, 10, v0
	v_mul_i32_i24_e32 v0, 0x400, v6
	v_sub_u32_e32 v0, v147, v0
	v_lshrrev_b32_e32 v1, 4, v0
	v_bitop3_b32 v0, v1, v0, 32 bitop3:0x6c
	v_ashrrev_i32_e32 v7, 31, v0
	v_lshrrev_b32_e32 v7, 26, v7
	v_add_u32_e32 v9, v0, v7
	v_lshlrev_b32_e32 v1, 3, v6
	v_ashrrev_i32_e32 v7, 6, v9
	v_and_b32_e32 v9, 0xc0, v9
	v_and_b32_e32 v1, 0x1fffff0, v1
	v_sub_u32_e32 v0, v0, v9
	s_lshl_b32 s36, s80, 8
	v_add_u32_e32 v1, v7, v1
	v_lshlrev_b32_e32 v8, 5, v6
	v_ashrrev_i16_sdwa v0, v138, sext(v0) dst_sel:DWORD dst_unused:UNUSED_PAD src0_sel:DWORD src1_sel:BYTE_0
	s_mul_i32 s38, s80, 0x2b0000
	v_add_u32_e32 v152, 0x10000, v139
	v_and_b32_e32 v8, 32, v8
	v_bfe_i32 v9, v0, 0, 16
	v_mul_lo_u32 v0, v1, s70
	s_mul_hi_i32 s39, s36, 0x2b00
	s_add_u32 s42, s52, s38
	v_readfirstlane_b32 s37, v152
	v_add_u32_e32 v153, 0x12000, v139
	v_or_b32_e32 v0, v0, v8
	s_addc_u32 s43, s53, s39
	s_mov_b32 m0, s37
	v_readfirstlane_b32 s37, v153
	s_mul_i32 s40, s79, 0x2b0000
	v_add_lshl_u32 v0, v0, v9, 1
	s_barrier
	global_load_lds_dwordx4 v128, s[42:43]
	s_mov_b32 m0, s37
	s_mul_hi_i32 s41, s81, 0x2b00
	s_add_u32 s44, s48, s40
	v_readfirstlane_b32 s37, v139
	global_load_lds_dwordx4 v0, s[42:43]
	s_addc_u32 s45, s49, s41
	s_mov_b32 m0, s37
	v_readfirstlane_b32 s37, v147
	s_bitset1_b32 s36, 7
	global_load_lds_dwordx4 v128, s[44:45]
	s_mov_b32 m0, s37
	s_mul_hi_i32 s37, s36, 0x2b00
	s_mulk_i32 s36, 0x2b00
	v_add_u32_e32 v158, 0x14000, v139
	s_add_u32 s46, s52, s36
	v_readfirstlane_b32 s36, v158
	v_add_u32_e32 v159, 0x16000, v139
	global_load_lds_dwordx4 v0, s[44:45]
	s_addc_u32 s47, s53, s37
	s_mov_b32 m0, s36
	v_readfirstlane_b32 s36, v159
	global_load_lds_dwordx4 v128, s[46:47]
	s_mov_b32 m0, s36
	s_or_b32 s36, s81, 0x80
	s_mul_hi_i32 s37, s36, 0x2b00
	s_mulk_i32 s36, 0x2b00
	v_add_u32_e32 v160, 0x4000, v139
	s_add_u32 s36, s48, s36
	v_readfirstlane_b32 s82, v160
	v_add_u32_e32 v161, 0x6000, v139
	global_load_lds_dwordx4 v0, s[46:47]
	s_addc_u32 s37, s49, s37
	s_mov_b32 m0, s82
	v_readfirstlane_b32 s82, v161
	global_load_lds_dwordx4 v128, s[36:37]
	s_mov_b32 m0, s82
	s_and_b64 vcc, exec, s[0:1]
	global_load_lds_dwordx4 v0, s[36:37]
	s_cbranch_vccnz .LBB0_1333
	s_barrier
